# residual prefetch across the grid barrier: in out-GEMM and attn-out the closing workgroup barrier moves below the 16 accumulator-init loads so waves 1-7 issue them while the grid sync is pending; rest
# speedup vs baseline: 1.0011x; 1.0011x over previous
; template <class Epi, class Sched, bool ALIGN_EPI = false, bool SP2 = false>
; __device__ __forceinline__ void gemm_phase(PG8_LAS unsigned char* lds, const Gemm g, const Sched& S, const Epi& E, const int wid) {
;     ...
;     Unit cur, nxt; int ui = 0;
;     if (!S.next(0, cur)) return;
; __device__ __forceinline__ void xcd_barrier(const XcdBarrier& b, bool leader) {
;     ...
;         __builtin_amdgcn_fence(__ATOMIC_ACQUIRE, "agent");
;         asm volatile("s_waitcnt vmcnt(0)" ::: "memory");
;     }
;     __syncthreads();
; }
.LBB0_388:
	s_or_b64 exec, exec, s[4:5]
	s_add_u32 s4, s90, 0x3100000
	s_addc_u32 s5, s91, 0
	v_writelane_b32 v250, s4, 30
	v_cndmask_b32_e64 v0, 0, 1, s[6:7]
	s_mov_b32 s49, 16
	v_writelane_b32 v250, s5, 31
	s_andn2_b64 vcc, exec, s[6:7]
	v_readlane_b32 s4, v250, 18
	s_bfe_u32 s48, s4, 0x20006
	s_lshl_b32 s4, s48, 5
	v_writelane_b32 v250, s4, 32
	v_cmp_ne_u32_e64 s[4:5], 1, v0
	s_nop 0
	v_writelane_b32 v250, s4, 33
	v_mbcnt_lo_u32_b32 v144, -1, 0
	v_mbcnt_hi_u32_b32 v144, -1, v144
	s_nop 1
	v_writelane_b32 v250, s5, 34
	s_lshl_b32 s4, s48, 12
	v_writelane_b32 v250, s4, 35
	s_cbranch_vccz .Lrh_work_out
	s_barrier
	s_branch .LBB0_429
.Lrh_work_out:
	s_ashr_i32 s4, s2, 31
	s_lshr_b32 s4, s4, 29
	s_add_i32 s7, s2, s4
	s_and_b32 s4, s7, -8
	s_sub_i32 s8, s2, s4
	s_cmp_gt_i32 s8, -1
	s_cbranch_scc0 .LBB0_391
	s_lshl_b32 s6, s8, 5
	s_cbranch_execz .LBB0_392
	s_branch .LBB0_393

; __device__ __forceinline__ float bf_lo(unsigned w) { return __uint_as_float(w << 16); }
; __device__ __forceinline__ float bf_hi(unsigned w) { return __uint_as_float(w & 0xffff0000u); }
; __device__ __forceinline__ int fresh_lane() { int l; asm volatile("v_mbcnt_lo_u32_b32 %0, -1, 0\n\tv_mbcnt_hi_u32_b32 %0, -1, %0" : "=v"(l)); return l; }
; __device__ __forceinline__ void acc_from_xb(AccT& acc, const bf16_t* xb, const Unit& u, int wr, int wc, int fr, int fq) {
;     const unsigned off0 = (unsigned)(u.pm * BM + wr * 64 + fr) * DM + u.pn * BM + wc * 32 + 8 * fq;
; #pragma unroll
;     for (int ai = 0; ai < 2; ++ai)
; #pragma unroll
;         for (int m = 0; m < 4; ++m)
; #pragma unroll
;             for (int bj = 0; bj < 2; ++bj) { const u32x4 w = *(const u32x4*)(xb + off0 + (unsigned)(ai * HALF + m * 16) * DM + bj * HALF);
;                 acc[ai][bj][m][0] = (f32x4){bf_lo(w.x), bf_hi(w.x), bf_lo(w.y), bf_hi(w.y)}; acc[ai][bj][m][1] = (f32x4){bf_lo(w.z), bf_hi(w.z), bf_lo(w.w), bf_hi(w.w)}; }
; template <class Epi, class Sched, bool ALIGN_EPI = false, bool SP2 = false>
; __device__ __forceinline__ void gemm_phase(PG8_LAS unsigned char* lds, const Gemm g, const Sched& S, const Epi& E, const int wid) {
;     const int lane = fresh_lane(), tid = wid * 64 + lane, wr = wid >> 2, wc = wid & 3, fr = lane & 15, fq = lane >> 4;
;     int nt = g.K / BK; asm volatile("" : "+s"(nt));
;     unsigned voffA[2], voffB[2];
; #pragma unroll
;     for (int i = 0; i < 2; ++i) { int R, C; stage_rc(tid * 16 + i * 8192, R, C); const int Rb = Epi::PERM ? ((R & ~31) + perm32(R & 31)) : R;
;         voffA[i] = (unsigned)(R * g.lda + C) * 2u; voffB[i] = (unsigned)(Rb * g.ldb + C) * 2u; }
;     const size_t kstep = (size_t)(BK * 2);
;     const size_t hstepA = (size_t)HALF * g.lda * 2, hstepB = (size_t)HALF * g.ldb * 2;
;     const size_t tstepA = 2 * hstepA, tstepB = 2 * hstepB;
;     const unsigned ldsw = (unsigned)wid * 1024u;
;     const int aoff = lds_byte(wr * 64 + fr, fq * 8), boff = lds_byte(wc * 32 + fr, fq * 8);
.LBB0_393:
	v_lshlrev_b32_e32 v145, 4, v144
	v_add_u32_e32 v0, s0, v145
	v_ashrrev_i32_e32 v1, 31, v0
	v_lshrrev_b32_e32 v1, 22, v1
	v_add_u32_e32 v1, v0, v1
	v_ashrrev_i32_e32 v149, 10, v1
	v_mul_i32_i24_e32 v1, 0x400, v149
	v_sub_u32_e32 v1, v0, v1
	v_lshrrev_b32_e32 v2, 4, v1
	v_bitop3_b32 v1, v2, v1, 32 bitop3:0x6c
	v_ashrrev_i32_e32 v3, 31, v1
	v_lshrrev_b32_e32 v3, 26, v3
	v_add_u32_e32 v3, v1, v3
	v_lshlrev_b32_e32 v2, 3, v149
	v_ashrrev_i32_e32 v150, 6, v3
	v_and_b32_e32 v3, 0xc0, v3
	v_and_b32_e32 v2, -16, v2
	v_sub_u32_e32 v1, v1, v3
	v_mov_b32_e32 v3, 1
	v_add_u32_e32 v2, v150, v2
	v_ashrrev_i16_sdwa v1, v3, sext(v1) dst_sel:DWORD dst_unused:UNUSED_PAD src0_sel:DWORD src1_sel:BYTE_0
	s_ashr_i32 s4, s7, 3
	v_lshlrev_b32_e32 v4, 5, v149
	v_bfe_i32 v151, v1, 0, 16
	v_lshlrev_b32_e32 v1, 1, v2
	v_lshrrev_b32_e32 v5, 2, v2
	v_and_b32_e32 v6, 3, v150
	s_mov_b32 s7, 0x1fffe0
	v_and_b32_e32 v4, 32, v4
	v_and_b32_e32 v1, 24, v1
	v_and_b32_e32 v5, 4, v5
	v_and_or_b32 v6, v2, s7, v6
	v_or3_b32 v1, v6, v5, v1
	v_add_lshl_u32 v4, v4, v151, 1
	v_add_u32_e32 v0, 0x2000, v0
	v_lshl_add_u32 v64, v1, 11, v4
	v_ashrrev_i32_e32 v1, 31, v0
	v_lshrrev_b32_e32 v1, 22, v1
	v_add_u32_e32 v1, v0, v1
	v_ashrrev_i32_e32 v152, 10, v1
	v_mul_i32_i24_e32 v1, 0x400, v152
	v_sub_u32_e32 v0, v0, v1
	v_lshrrev_b32_e32 v1, 4, v0
	v_bitop3_b32 v0, v1, v0, 32 bitop3:0x6c
	v_lshl_add_u32 v128, v2, 11, v4
	v_ashrrev_i32_e32 v2, 31, v0
	v_lshrrev_b32_e32 v2, 26, v2
	v_add_u32_e32 v2, v0, v2
	v_ashrrev_i32_e32 v153, 6, v2
	v_and_b32_e32 v2, 0xffc0, v2
	s_add_u32 s5, s90, 0x600000
	v_sub_u32_e32 v0, v0, v2
	s_addc_u32 s54, s91, 0
	v_lshrrev_b16_e32 v2, 7, v0
	s_add_i32 s4, s6, s4
	v_lshlrev_b32_e32 v1, 3, v152
	v_and_b32_e32 v2, 1, v2
	s_ashr_i32 s6, s4, 31
	v_and_b32_e32 v1, -16, v1
	v_add_u16_e32 v0, v0, v2
	s_lshr_b32 s6, s6, 27
	v_add_u32_e32 v1, v153, v1
	v_ashrrev_i16_sdwa v0, v3, sext(v0) dst_sel:DWORD dst_unused:UNUSED_PAD src0_sel:DWORD src1_sel:BYTE_0
	v_and_b32_e32 v3, 3, v153
	s_add_i32 s6, s4, s6
	v_and_or_b32 v3, v1, s7, v3
	s_ashr_i32 s7, s6, 5
	s_andn2_b32 s6, s6, 31
	s_sub_i32 s4, s4, s6
	s_bfe_i32 s6, s4, 0x80000
	s_bfe_u32 s6, s6, 0x3000c
	s_add_i32 s8, s4, s6
	s_bfe_i32 s6, s8, 0x80000
	s_and_b32 s8, s8, 0xf8
	s_sub_i32 s4, s4, s8
	v_lshlrev_b32_e32 v4, 5, v152
	v_bfe_i32 v154, v0, 0, 16
	v_lshlrev_b32_e32 v0, 1, v1
	v_lshrrev_b32_e32 v2, 2, v1
	s_lshl_b32 s7, s7, 3
	s_sext_i32_i8 s4, s4
	v_and_b32_e32 v4, 32, v4
	v_and_b32_e32 v0, 24, v0
	v_and_b32_e32 v2, 4, v2
	s_add_i32 s10, s7, s4
	v_or3_b32 v0, v3, v2, v0
	v_add_lshl_u32 v2, v4, v154, 1
	s_lshl_b32 s7, s10, 8
	v_lshl_add_u32 v132, v0, 11, v2
	v_and_b32_e32 v146, 15, v144
	v_ashrrev_i32_e32 v0, 1, v144
	s_sext_i32_i16 s9, s6
	s_add_i32 s7, s7, s72
	v_lshl_add_u32 v130, v1, 11, v2
	v_and_b32_e32 v0, -8, v0
	s_ashr_i32 s4, s9, 3
	v_or_b32_e32 v1, s7, v146
	v_readlane_b32 s8, v250, 32
	v_lshlrev_b32_e32 v1, 10, v1
	s_lshl_b32 s7, s4, 8
	v_add_u32_e32 v147, s8, v0
	v_add3_u32 v134, s7, v147, v1
	v_mov_b32_e32 v135, 0
	v_lshl_add_u64 v[0:1], v[134:135], 1, s[94:95]
	s_mov_b32 s7, 0x8000
	v_add_co_u32_e32 v2, vcc, s7, v0
	s_mov_b32 s7, 0x10000
	s_nop 0
	v_addc_co_u32_e32 v3, vcc, 0, v1, vcc
	global_load_dwordx4 v[60:63], v[0:1], off
	global_load_dwordx4 v[56:59], v[0:1], off offset:256
	global_load_dwordx4 v[52:55], v[2:3], off
	global_load_dwordx4 v[48:51], v[2:3], off offset:256
	v_add_co_u32_e32 v2, vcc, s7, v0
	s_mov_b32 s7, 0x18000
	s_nop 0
	v_addc_co_u32_e32 v3, vcc, 0, v1, vcc
	global_load_dwordx4 v[44:47], v[2:3], off
	global_load_dwordx4 v[40:43], v[2:3], off offset:256
	v_add_co_u32_e32 v2, vcc, s7, v0
	s_mov_b32 s7, 0x40000
	s_nop 0
	v_addc_co_u32_e32 v3, vcc, 0, v1, vcc
	global_load_dwordx4 v[36:39], v[2:3], off
	global_load_dwordx4 v[28:31], v[2:3], off offset:256
	v_add_co_u32_e32 v2, vcc, s7, v0
	s_mov_b32 s7, 0x48000
	s_nop 0
	v_addc_co_u32_e32 v3, vcc, 0, v1, vcc
	global_load_dwordx4 v[20:23], v[2:3], off
	global_load_dwordx4 v[8:11], v[2:3], off offset:256
	v_add_co_u32_e32 v2, vcc, s7, v0
	s_mov_b32 s7, 0x50000
	s_nop 0
	v_addc_co_u32_e32 v3, vcc, 0, v1, vcc
	s_ashr_i32 s11, s10, 31
	s_lshr_b32 s6, s9, 3
	global_load_dwordx4 v[12:15], v[2:3], off
	global_load_dwordx4 v[32:35], v[2:3], off offset:256
	v_add_co_u32_e32 v2, vcc, s7, v0
	s_lshl_b64 s[8:9], s[10:11], 19
	s_nop 0
	v_addc_co_u32_e32 v3, vcc, 0, v1, vcc
	s_mov_b32 s7, 0x58000
	s_add_u32 s22, s92, s8
	v_add_co_u32_e32 v0, vcc, s7, v0
	s_addc_u32 s23, s93, s9
	s_bfe_i64 s[6:7], s[6:7], 0x100000
	s_lshl_b64 s[6:7], s[6:7], 19
	s_add_u32 s24, s5, s6
	s_addc_u32 s25, s54, s7
	s_add_i32 s11, s0, 0
	v_addc_co_u32_e32 v1, vcc, 0, v1, vcc
	s_add_i32 m0, s11, 0x10000
	global_load_dwordx4 v[24:27], v[2:3], off
	global_load_dwordx4 v[16:19], v[2:3], off offset:256
	global_load_dwordx4 v[4:7], v[0:1], off
	s_nop 0
	global_load_dwordx4 v[0:3], v[0:1], off offset:256
	v_mov_b32_e32 v134, v64
	s_barrier
	global_load_lds_dwordx4 v64, s[24:25]
	s_add_i32 m0, s11, 0x12000
	s_add_u32 s6, s24, 0x40000
	global_load_lds_dwordx4 v132, s[24:25]
	s_addc_u32 s7, s25, 0
	s_add_i32 m0, s11, 0x14000
	s_add_i32 s55, s11, 0x2000
	global_load_lds_dwordx4 v64, s[6:7]
	s_add_i32 m0, s11, 0x16000
	v_mov_b32_e32 v133, v135
	global_load_lds_dwordx4 v132, s[6:7]
	s_mov_b32 m0, s11
	s_add_u32 s6, s22, 0x40000
	global_load_lds_dwordx4 v128, s[22:23]
	s_mov_b32 m0, s55
	s_addc_u32 s7, s23, 0
	s_add_i32 s56, s11, 0x4000
	global_load_lds_dwordx4 v130, s[22:23]
	s_mov_b32 m0, s56
	s_add_i32 s57, s11, 0x6000
	global_load_lds_dwordx4 v128, s[6:7]
	s_mov_b32 m0, s57
	v_mov_b32_e32 v129, v135
	global_load_lds_dwordx4 v130, s[6:7]
	v_mov_b32_e32 v131, v135
	s_mov_b32 s58, 0
	v_lshl_add_u64 v[142:143], s[24:25], 0, v[134:135]
	v_lshl_add_u64 v[140:141], s[24:25], 0, v[132:133]
	v_lshl_add_u64 v[138:139], s[22:23], 0, v[128:129]
	s_cmp_lg_u32 s1, 1
	v_lshl_add_u64 v[136:137], s[22:23], 0, v[130:131]
	s_cbranch_scc1 .LBB0_395
	s_barrier

; __device__ __forceinline__ float bf_lo(unsigned w) { return __uint_as_float(w << 16); }
; __device__ __forceinline__ float bf_hi(unsigned w) { return __uint_as_float(w & 0xffff0000u); }
; __device__ __forceinline__ int fresh_lane() { int l; asm volatile("v_mbcnt_lo_u32_b32 %0, -1, 0\n\tv_mbcnt_hi_u32_b32 %0, -1, %0" : "=v"(l)); return l; }
; __device__ __forceinline__ void acc_from_xb(AccT& acc, const bf16_t* xb, const Unit& u, int wr, int wc, int fr, int fq) {
;     const unsigned off0 = (unsigned)(u.pm * BM + wr * 64 + fr) * DM + u.pn * BM + wc * 32 + 8 * fq;
; #pragma unroll
;     for (int ai = 0; ai < 2; ++ai)
; #pragma unroll
;         for (int m = 0; m < 4; ++m)
; #pragma unroll
;             for (int bj = 0; bj < 2; ++bj) { const u32x4 w = *(const u32x4*)(xb + off0 + (unsigned)(ai * HALF + m * 16) * DM + bj * HALF);
;                 acc[ai][bj][m][0] = (f32x4){bf_lo(w.x), bf_hi(w.x), bf_lo(w.y), bf_hi(w.y)}; acc[ai][bj][m][1] = (f32x4){bf_lo(w.z), bf_hi(w.z), bf_lo(w.w), bf_hi(w.w)}; }
; template <class Epi, class Sched, bool ALIGN_EPI = false, bool SP2 = false>
; __device__ __forceinline__ void gemm_phase(PG8_LAS unsigned char* lds, const Gemm g, const Sched& S, const Epi& E, const int wid) {
;     const int lane = fresh_lane(), tid = wid * 64 + lane, wr = wid >> 2, wc = wid & 3, fr = lane & 15, fq = lane >> 4;
;     int nt = g.K / BK; asm volatile("" : "+s"(nt));
;     unsigned voffA[2], voffB[2];
; #pragma unroll
;     for (int i = 0; i < 2; ++i) { int R, C; stage_rc(tid * 16 + i * 8192, R, C); const int Rb = Epi::PERM ? ((R & ~31) + perm32(R & 31)) : R;
;         voffA[i] = (unsigned)(R * g.lda + C) * 2u; voffB[i] = (unsigned)(Rb * g.ldb + C) * 2u; }
;     const size_t kstep = (size_t)(BK * 2);
;     const size_t hstepA = (size_t)HALF * g.lda * 2, hstepB = (size_t)HALF * g.ldb * 2;
;     const size_t tstepA = 2 * hstepA, tstepB = 2 * hstepB;
;     const unsigned ldsw = (unsigned)wid * 1024u;
;     const int aoff = lds_byte(wr * 64 + fr, fq * 8), boff = lds_byte(wc * 32 + fr, fq * 8);
.LBB0_817:
	s_or_b64 exec, exec, s[4:5]
	v_readlane_b32 s8, v250, 33
	v_readlane_b32 s9, v250, 34
	s_mov_b32 s5, 16
	s_and_b64 vcc, exec, s[8:9]
	v_mbcnt_lo_u32_b32 v138, -1, 0
	v_mbcnt_hi_u32_b32 v138, -1, v138
	s_cbranch_vccz .Lrh_work_attn
	s_barrier
	s_branch .LBB0_855
.Lrh_work_attn:
	v_lshlrev_b32_e32 v139, 4, v138
	v_add_u32_e32 v1, s0, v139
	v_add_u32_e32 v2, 0x2000, v1
	v_ashrrev_i32_e32 v3, 31, v2
	v_lshrrev_b32_e32 v3, 22, v3
	v_add_u32_e32 v3, v2, v3
	v_ashrrev_i32_e32 v136, 10, v3
	v_mul_i32_i24_e32 v3, 0x400, v136
	v_sub_u32_e32 v2, v2, v3
	v_lshrrev_b32_e32 v3, 4, v2
	v_bitop3_b32 v2, v3, v2, 32 bitop3:0x6c
	v_ashrrev_i32_e32 v3, 31, v2
	v_lshrrev_b32_e32 v3, 26, v3
	v_add_u32_e32 v3, v2, v3
	v_ashrrev_i32_e32 v137, 6, v3
	v_lshlrev_b32_e32 v4, 3, v136
	v_and_b32_e32 v3, 0xffc0, v3
	v_and_b32_e32 v4, -16, v4
	v_sub_u32_e32 v2, v2, v3
	v_add_u32_e32 v4, v137, v4
	v_lshrrev_b16_e32 v3, 7, v2
	v_and_b32_e32 v5, 3, v137
	s_mov_b32 s4, 0x1fffe0
	v_lshrrev_b32_e32 v6, 2, v4
	v_lshlrev_b32_e32 v7, 1, v4
	v_and_b32_e32 v3, 1, v3
	v_and_or_b32 v5, v4, s4, v5
	v_and_b32_e32 v6, 4, v6
	v_and_b32_e32 v7, 24, v7
	v_add_u16_e32 v2, v2, v3
	v_or3_b32 v5, v5, v6, v7
	v_lshlrev_b32_e32 v6, 5, v136
	v_ashrrev_i16_sdwa v2, v167, sext(v2) dst_sel:DWORD dst_unused:UNUSED_PAD src0_sel:DWORD src1_sel:BYTE_0
	v_and_b32_e32 v6, 32, v6
	v_bfe_i32 v143, v2, 0, 16
	v_add_lshl_u32 v2, v6, v143, 1
	v_lshl_add_u32 v128, v5, 11, v2
	v_lshl_add_u32 v130, v4, 11, v2
	v_ashrrev_i32_e32 v2, 31, v1
	v_lshrrev_b32_e32 v2, 22, v2
	v_add_u32_e32 v2, v1, v2
	v_ashrrev_i32_e32 v134, 10, v2
	v_mul_i32_i24_e32 v2, 0x400, v134
	v_sub_u32_e32 v1, v1, v2
	v_lshrrev_b32_e32 v2, 4, v1
	v_bitop3_b32 v1, v2, v1, 32 bitop3:0x6c
	v_ashrrev_i32_e32 v2, 31, v1
	v_lshrrev_b32_e32 v2, 26, v2
	v_add_u32_e32 v2, v1, v2
	v_lshlrev_b32_e32 v3, 3, v134
	v_ashrrev_i32_e32 v135, 6, v2
	v_and_b32_e32 v3, -16, v3
	v_add_u32_e32 v3, v135, v3
	v_and_b32_e32 v4, 3, v135
	v_lshrrev_b32_e32 v5, 2, v3
	v_lshlrev_b32_e32 v6, 1, v3
	v_and_b32_e32 v2, 0xc0, v2
	v_and_or_b32 v4, v3, s4, v4
	v_and_b32_e32 v5, 4, v5
	v_and_b32_e32 v6, 24, v6
	v_sub_u32_e32 v1, v1, v2
	v_or3_b32 v4, v4, v5, v6
	v_lshlrev_b32_e32 v5, 5, v134
	v_ashrrev_i16_sdwa v1, v167, sext(v1) dst_sel:DWORD dst_unused:UNUSED_PAD src0_sel:DWORD src1_sel:BYTE_0
	v_and_b32_e32 v5, 32, v5
	v_bfe_i32 v160, v1, 0, 16
	v_and_b32_e32 v140, 15, v138
	v_ashrrev_i32_e32 v0, 1, v138
	v_add_lshl_u32 v1, v5, v160, 1
	v_readlane_b32 s4, v249, 29
	v_and_b32_e32 v0, -8, v0
	v_lshl_add_u32 v146, v4, 11, v1
	v_lshl_add_u32 v132, v3, 11, v1
	v_or_b32_e32 v1, s4, v140
	v_readlane_b32 s4, v250, 32
	v_lshlrev_b32_e32 v1, 10, v1
	s_add_i32 s64, s0, 0
	v_add_u32_e32 v141, s4, v0
	v_readlane_b32 s4, v249, 30
	v_readlane_b32 s8, v249, 43
	s_add_i32 m0, s64, 0x10000
	v_add3_u32 v0, s4, v141, v1
	v_mov_b32_e32 v1, v147
	v_lshl_add_u64 v[0:1], v[0:1], 1, s[94:95]
	v_add_co_u32_e32 v2, vcc, s39, v0
	global_load_dwordx4 v[60:63], v[0:1], off
	global_load_dwordx4 v[56:59], v[0:1], off offset:256
	v_addc_co_u32_e32 v3, vcc, 0, v1, vcc
	global_load_dwordx4 v[52:55], v[2:3], off
	global_load_dwordx4 v[48:51], v[2:3], off offset:256
	v_add_co_u32_e32 v2, vcc, s52, v0
	s_mov_b32 s4, 0x40000
	s_nop 0
	v_addc_co_u32_e32 v3, vcc, 0, v1, vcc
	global_load_dwordx4 v[44:47], v[2:3], off
	global_load_dwordx4 v[40:43], v[2:3], off offset:256
	v_add_co_u32_e32 v2, vcc, s73, v0
	v_readlane_b32 s9, v249, 44
	s_nop 0
	v_addc_co_u32_e32 v3, vcc, 0, v1, vcc
	global_load_dwordx4 v[36:39], v[2:3], off
	global_load_dwordx4 v[20:23], v[2:3], off offset:256
	v_add_co_u32_e32 v2, vcc, s4, v0
	s_mov_b32 s4, 0x48000
	s_nop 0
	v_addc_co_u32_e32 v3, vcc, 0, v1, vcc
	global_load_dwordx4 v[16:19], v[2:3], off
	global_load_dwordx4 v[8:11], v[2:3], off offset:256
	v_add_co_u32_e32 v2, vcc, s4, v0
	s_mov_b32 s4, 0x50000
	s_nop 0
	v_addc_co_u32_e32 v3, vcc, 0, v1, vcc
	global_load_dwordx4 v[12:15], v[2:3], off
	global_load_dwordx4 v[32:35], v[2:3], off offset:256
	v_add_co_u32_e32 v2, vcc, s4, v0
	s_mov_b32 s4, 0x58000
	s_nop 0
	v_addc_co_u32_e32 v3, vcc, 0, v1, vcc
	v_add_co_u32_e32 v0, vcc, s4, v0
	global_load_dwordx4 v[28:31], v[2:3], off
	global_load_dwordx4 v[24:27], v[2:3], off offset:256
	v_addc_co_u32_e32 v1, vcc, 0, v1, vcc
	global_load_dwordx4 v[4:7], v[0:1], off
	s_nop 0
	global_load_dwordx4 v[0:3], v[0:1], off offset:256
	s_add_i32 s65, s64, 0x2000
	s_barrier
	global_load_lds_dwordx4 v146, s[8:9]
	s_add_i32 m0, s64, 0x12000
	s_add_i32 s66, s64, 0x4000
	global_load_lds_dwordx4 v128, s[8:9]
	v_readlane_b32 s8, v249, 37
	s_add_i32 m0, s64, 0x14000
	v_readlane_b32 s9, v249, 38
	s_add_i32 s67, s64, 0x6000
	s_nop 3
	global_load_lds_dwordx4 v146, s[8:9]
	s_add_i32 m0, s64, 0x16000
	s_nop 0
	global_load_lds_dwordx4 v128, s[8:9]
	v_readlane_b32 s8, v249, 39
	s_mov_b32 m0, s64
	v_readlane_b32 s9, v249, 40
	s_nop 4
	global_load_lds_dwordx4 v132, s[8:9]
	s_mov_b32 m0, s65
	s_nop 0
	global_load_lds_dwordx4 v130, s[8:9]
	v_readlane_b32 s8, v249, 41
	s_mov_b32 m0, s66
	v_readlane_b32 s9, v249, 42
	s_nop 4
	global_load_lds_dwordx4 v132, s[8:9]
	s_mov_b32 m0, s67
	s_nop 0
	global_load_lds_dwordx4 v130, s[8:9]
	v_readlane_b32 s8, v248, 1
	v_readlane_b32 s9, v248, 2
	s_andn2_b64 vcc, exec, s[8:9]
	s_cbranch_vccnz .LBB0_820
	s_barrier
